# FFN-out fused epilogue pass 1: first residual pair of the second row half issued together with the first half's loads
# baseline (speedup 1.0000x reference)
.LBB0_702:
	s_andn2_b64 vcc, exec, s[50:51]
	s_cbranch_vccnz .LBB0_740
	v_lshlrev_b32_e32 v250, 2, v182
	v_mov_b32_e32 v251, 0
	v_lshl_add_u64 v[250:251], v[250:251], 0, s[76:77]
	global_load_dwordx4 v[234:237], v[250:251], off
	global_load_dwordx4 v[238:241], v[250:251], off offset:16
	global_load_dwordx4 v[242:245], v[250:251], off offset:512
	global_load_dwordx4 v[246:249], v[250:251], off offset:528
	v_lshlrev_b32_e32 v130, 1, v182
	v_lshl_add_u32 v170, v180, 11, v130
	v_or_b32_e32 v188, 0x100, v170
	global_load_dwordx4 v[190:193], v170, s[40:41]
	global_load_dwordx4 v[194:197], v188, s[40:41]
	v_add_u32_e32 v186, 0x8000, v170
	v_add_u32_e32 v184, 0x8100, v170
	v_add_u32_e32 v160, 0x10000, v170
	v_add_u32_e32 v158, 0x10100, v170
	v_add_u32_e32 v156, 0x18000, v170
	v_add_u32_e32 v154, 0x18100, v170
	global_load_dwordx4 v[150:153], v186, s[40:41]
	global_load_dwordx4 v[146:149], v184, s[40:41]
	global_load_dwordx4 v[142:145], v160, s[40:41]
	global_load_dwordx4 v[138:141], v158, s[40:41]
	global_load_dwordx4 v[134:137], v156, s[40:41]
	global_load_dwordx4 v[130:133], v154, s[40:41]
	v_add_u32_e32 v250, 0x40000, v170
	v_add_u32_e32 v251, 0x40100, v170
	global_load_dwordx4 v[220:223], v250, s[40:41]
	global_load_dwordx4 v[224:227], v251, s[40:41]
	v_and_b32_e32 v157, 64, v211
	v_xor_b32_e32 v155, 16, v211
	v_add_u32_e32 v157, 64, v157
	v_cmp_lt_i32_e32 vcc, v155, v157
	s_waitcnt vmcnt(2)
	v_lshlrev_b32_e32 v198, 16, v190
	v_and_b32_e32 v199, 0xffff0000, v190
	v_lshlrev_b32_e32 v190, 16, v191
	v_and_b32_e32 v191, 0xffff0000, v191
	v_lshlrev_b32_e32 v202, 16, v194
	v_and_b32_e32 v203, 0xffff0000, v194
	v_lshlrev_b32_e32 v194, 16, v195
	v_and_b32_e32 v195, 0xffff0000, v195
	v_lshlrev_b32_e32 v200, 16, v192
	v_and_b32_e32 v201, 0xffff0000, v192
	v_pk_add_f32 v[128:129], v[128:129], v[190:191]
	v_pk_add_f32 v[126:127], v[126:127], v[198:199]
	v_lshlrev_b32_e32 v204, 16, v196
	v_and_b32_e32 v205, 0xffff0000, v196
	v_pk_add_f32 v[112:113], v[112:113], v[194:195]
	v_pk_add_f32 v[110:111], v[110:111], v[202:203]
	v_lshlrev_b32_e32 v192, 16, v193
	v_and_b32_e32 v193, 0xffff0000, v193
	v_pk_add_f32 v[122:123], v[122:123], v[200:201]
	v_lshlrev_b32_e32 v196, 16, v197
	v_and_b32_e32 v197, 0xffff0000, v197
	v_mul_f32_e32 v159, v127, v127
	v_mul_f32_e32 v161, v129, v129
	v_pk_add_f32 v[106:107], v[106:107], v[204:205]
	v_mul_f32_e32 v185, v111, v111
	v_mul_f32_e32 v187, v113, v113
	v_pk_add_f32 v[124:125], v[124:125], v[192:193]
	v_mul_f32_e32 v181, v123, v123
	v_pk_add_f32 v[108:109], v[108:109], v[196:197]
	v_fmac_f32_e32 v159, v126, v126
	v_fmac_f32_e32 v161, v128, v128
	v_mul_f32_e32 v189, v107, v107
	v_fmac_f32_e32 v185, v110, v110
	v_fmac_f32_e32 v187, v112, v112
	v_mul_f32_e32 v183, v125, v125
	v_fmac_f32_e32 v181, v122, v122
	v_mul_f32_e32 v190, v109, v109
	v_add_f32_e32 v159, v159, v161
	v_fmac_f32_e32 v189, v106, v106
	v_add_f32_e32 v161, v185, v187
	v_fmac_f32_e32 v183, v124, v124
	v_add_f32_e32 v159, v181, v159
	v_add_f32_e32 v161, v189, v161
	v_fmac_f32_e32 v190, v108, v108
	v_cndmask_b32_e32 v155, v211, v155, vcc
	v_add_f32_e32 v159, v183, v159
	v_add_f32_e32 v161, v190, v161
	v_lshlrev_b32_e32 v155, 2, v155
	v_add_f32_e32 v159, v159, v161
	v_mov_b32_e32 v161, v159
	s_nop 1
	v_permlane16_swap_b32_e32 v161, v159
	s_nop 1
	v_xor_b32_e32 v181, 32, v211
	v_cmp_lt_i32_e32 vcc, v181, v157
	s_waitcnt lgkmcnt(0)
	v_add_f32_e32 v159, v159, v161
	v_cndmask_b32_e32 v157, v211, v181, vcc
	v_lshlrev_b32_e32 v157, 2, v157
	v_mov_b32_e32 v161, v159
	s_nop 1
	v_permlane32_swap_b32_e32 v161, v159
	s_nop 1
	s_and_saveexec_b64 s[50:51], s[4:5]
	s_cbranch_execz .LBB0_705
	s_waitcnt lgkmcnt(0)
	v_add_f32_e32 v159, v159, v161
	ds_write_b32 v218, v159

.LBB0_711:
	s_or_b64 exec, exec, s[50:51]
	v_add_u32_e32 v200, 0x48000, v170
	v_add_u32_e32 v198, 0x48100, v170
	v_add_u32_e32 v196, 0x50000, v170
	v_add_u32_e32 v194, 0x50100, v170
	v_add_u32_e32 v192, 0x58000, v170
	v_add_u32_e32 v190, 0x58100, v170
	global_load_dwordx4 v[150:153], v200, s[40:41]
	global_load_dwordx4 v[146:149], v198, s[40:41]
	global_load_dwordx4 v[142:145], v196, s[40:41]
	global_load_dwordx4 v[138:141], v194, s[40:41]
	global_load_dwordx4 v[134:137], v192, s[40:41]
	s_waitcnt lgkmcnt(0)
	global_load_dwordx4 v[130:133], v190, s[40:41]
	s_waitcnt vmcnt(7)
	v_lshlrev_b32_e32 v206, 16, v220
	v_and_b32_e32 v207, 0xffff0000, v220
	v_lshlrev_b32_e32 v220, 16, v221
	v_and_b32_e32 v221, 0xffff0000, v221
	s_waitcnt vmcnt(6)
	v_lshlrev_b32_e32 v230, 16, v224
	v_and_b32_e32 v231, 0xffff0000, v224
	v_lshlrev_b32_e32 v224, 16, v225
	v_and_b32_e32 v225, 0xffff0000, v225
	v_lshlrev_b32_e32 v228, 16, v222
	v_and_b32_e32 v229, 0xffff0000, v222
	v_lshlrev_b32_e32 v232, 16, v226
	v_and_b32_e32 v233, 0xffff0000, v226
	v_pk_add_f32 v[64:65], v[64:65], v[220:221]
	v_pk_add_f32 v[62:63], v[62:63], v[206:207]
	v_pk_add_f32 v[48:49], v[48:49], v[224:225]
	v_pk_add_f32 v[46:47], v[46:47], v[230:231]
	v_lshlrev_b32_e32 v222, 16, v223
	v_and_b32_e32 v223, 0xffff0000, v223
	v_lshlrev_b32_e32 v226, 16, v227
	v_and_b32_e32 v227, 0xffff0000, v227
	v_pk_add_f32 v[58:59], v[58:59], v[228:229]
	v_pk_add_f32 v[42:43], v[42:43], v[232:233]
	v_mul_f32_e32 v159, v63, v63
	v_mul_f32_e32 v161, v65, v65
	v_mul_f32_e32 v185, v47, v47
	v_mul_f32_e32 v187, v49, v49
	v_pk_add_f32 v[60:61], v[60:61], v[222:223]
	v_pk_add_f32 v[44:45], v[44:45], v[226:227]
	v_mul_f32_e32 v181, v59, v59
	v_mul_f32_e32 v189, v43, v43
	v_fmac_f32_e32 v159, v62, v62
	v_fmac_f32_e32 v161, v64, v64
	v_fmac_f32_e32 v185, v46, v46
	v_fmac_f32_e32 v187, v48, v48
	v_mul_f32_e32 v183, v61, v61
	v_mul_f32_e32 v191, v45, v45
	v_fmac_f32_e32 v181, v58, v58
	v_fmac_f32_e32 v189, v42, v42
	v_add_f32_e32 v159, v159, v161
	v_add_f32_e32 v161, v185, v187
	v_fmac_f32_e32 v183, v60, v60
	v_fmac_f32_e32 v191, v44, v44
	v_add_f32_e32 v159, v181, v159
	v_add_f32_e32 v161, v189, v161
	v_add_f32_e32 v159, v183, v159
	v_add_f32_e32 v161, v191, v161
	v_add_f32_e32 v159, v159, v161
	v_mov_b32_e32 v161, v159
	s_nop 1
	v_permlane16_swap_b32_e32 v161, v159
	s_nop 1
	s_waitcnt lgkmcnt(0)
	v_add_f32_e32 v159, v159, v161
	v_mov_b32_e32 v161, v159
	s_nop 1
	v_permlane32_swap_b32_e32 v161, v159
	s_nop 1
	s_and_saveexec_b64 s[50:51], s[4:5]
	s_cbranch_execz .LBB0_713
	s_waitcnt lgkmcnt(0)
	v_add_f32_e32 v159, v159, v161
	ds_write_b32 v218, v159 offset:2048
